# dilated attention: per-wave rotation of the key-tile order so that waves sharing a key tile request it in the same step; on top of scalar-base GEMM loads
# speedup vs baseline: 1.0116x; 1.0021x over previous
; #define ATT_Q_DMA() do { unsigned qo_ = kD - klb; asm volatile("" : "+v"(qo_) :: "memory");     \
;         _Pragma("unroll") for (int c = 0; c < 8; ++c) \
;         __builtin_amdgcn_global_load_lds((const unsigned*)(qb + 1024 * c + (qo_ ^ (unsigned)((c & 3) << 6))), (ALDS unsigned*)(klb + 1024u * c), 16, 0, 0); } while (0)
; #define DIL_LOAD(t, dst, src) do { const int mk0_ = m0 - 64 + 32 * (t); \
;             _Pragma("unroll") for (int c = 0; c < 8; ++c) { const int uo_ = (rbase + mk0_ + 4 * c) * (int)(PITCH * 2); dst[c] = *(const u32x4*)((src + (long)uo_) + lane_off); } } while (0)
; __device__ __forceinline__ void dil_phase(const bf16* qkv, bf16* scratch, bf16* merged, ldsp lds, int vcu, int G, int tid_in) {
;     ...
;             const int it = k * 8 + wave, g = it >> 4, sub = it & 15;
;             const int shift = 2 * g, L = 16384 >> shift;
;             const int r = (g == 0) ? 0 : (g == 1) ? (sub & 3) : sub;
;             const int m0 = (g == 0) ? (T0 + 32 * sub) : (g == 1) ? ((T0 >> 2) + 32 * (sub >> 2)) : (T0 >> 4);
;             const int mq = m0 + r32, tq = (mq << shift) + r;
;             const int rbase = tokb + (r << (14 - shift));
;             const char* qb = (const char*)(qkv + (size_t)((g * 3 + 0) * 8 + head) * PLANE + (size_t)(rbase + m0) * PITCH);
;             ATT_Q_DMA();
;             const char* kb = (const char*)(qkv + (size_t)((g * 3 + 1) * 8 + head) * PLANE); const char* vb = (const char*)(qkv + (size_t)((g * 3 + 2) * 8 + head) * PLANE);
;             const unsigned lane_off = (unsigned)((lane >> 4) * (int)(PITCH * 2) + (lane & 15) * 16);
;             St S; S.m = NEGBIG; S.l = 0.f;
; #pragma unroll
;             for (int db = 0; db < 4; ++db)
; #pragma unroll
;                 for (int i = 0; i < 16; ++i) S.O[db][i] = 0.f;
;             u32x4 kr[8], vr[8]; f32x16 st;
;     ...
;             DIL_LOAD(0, kr, kb); DIL_LOAD(0, vr, vb);
;             bf16x8 qf[8];
;             ATT_Q_FRAGS();
.LBB0_682:
	s_lshr_b32 s100, s85, 5
	s_lshl_b32 s100, s100, 2
	s_add_i32 s100, s100, 2
	s_mul_i32 s101, s100, 0xcccd
	s_lshr_b32 s101, s101, 18
	s_mul_i32 s101, s101, 5
	s_sub_i32 s100, s100, s101
	s_lshl_b32 s52, s84, 1
	s_lshr_b32 s86, 0x4000, s52
	s_and_b32 s26, s26, 15
	s_and_b64 s[12:13], s[12:13], exec
	s_cselect_b32 s12, s58, s26
	s_and_b64 s[10:11], s[10:11], exec
	s_cselect_b32 s53, 0, s12
	s_sub_i32 s10, 14, s52
	s_mul_i32 s87, s84, 24
	s_lshl_b32 s33, s53, s10
	s_or_b32 s10, s87, s71
	s_ashr_i32 s11, s10, 31
	s_add_i32 s12, s33, s74
	s_lshl_b64 s[10:11], s[10:11], 23
	s_add_u32 s26, s34, s10
	s_addc_u32 s27, s35, s11
	s_add_i32 s10, s85, s12
	s_ashr_i32 s11, s10, 31
	s_lshl_b64 s[12:13], s[10:11], 8
	s_add_u32 s12, s26, s12
	v_mov_b32_e32 v0, v214
	s_addc_u32 s13, s27, s13
	v_mov_b32_e32 v5, v1
	v_xor_b32_e32 v4, 64, v0
	s_mov_b32 m0, s57
	v_lshl_add_u64 v[4:5], s[12:13], 0, v[4:5]
	s_mov_b64 s[26:27], 0x400
	global_load_lds_dwordx4 v0, s[12:13]
	v_lshl_add_u64 v[6:7], v[4:5], 0, s[26:27]
	s_add_i32 m0, s57, 0x400
	s_mov_b64 s[26:27], 0x800
	global_load_lds_dwordx4 v[6:7], off
	v_xor_b32_e32 v6, 0x80, v0
	v_mov_b32_e32 v7, v1
	v_lshl_add_u64 v[6:7], s[12:13], 0, v[6:7]
	v_lshl_add_u64 v[2:3], s[12:13], 0, v[0:1]
	v_lshl_add_u64 v[8:9], v[6:7], 0, s[26:27]
	s_add_i32 m0, s57, 0x800
	v_xor_b32_e32 v0, 0xc0, v0
	global_load_lds_dwordx4 v[8:9], off
	v_lshl_add_u64 v[8:9], s[12:13], 0, v[0:1]
	s_mov_b64 s[12:13], 0xc00
	v_lshl_add_u64 v[10:11], v[8:9], 0, s[12:13]
	s_add_i32 m0, s57, 0xc00
	s_mov_b64 s[12:13], 0x1000
	global_load_lds_dwordx4 v[10:11], off
	v_lshl_add_u64 v[2:3], v[2:3], 0, s[12:13]
	s_add_i32 m0, s57, 0x1000
	s_add_i32 s12, s75, s87
	global_load_lds_dwordx4 v[2:3], off
	v_lshl_add_u64 v[2:3], v[4:5], 0, s[46:47]
	s_add_i32 m0, s57, 0x1400
	s_ashr_i32 s13, s12, 31
	s_add_i32 s26, s76, s87
	s_lshl_b32 s87, s10, 8
	s_mul_i32 s101, s100, 0x2000
	s_add_i32 s87, s87, s101
	global_load_lds_dwordx4 v[2:3], off
	v_lshl_add_u64 v[2:3], v[6:7], 0, s[48:49]
	s_add_i32 m0, s57, 0x1800
	s_lshl_b64 s[12:13], s[12:13], 23
	s_add_i32 s10, s87, 0xffffc000
	global_load_lds_dwordx4 v[2:3], off
	v_lshl_add_u64 v[2:3], v[8:9], 0, s[50:51]
	s_add_i32 m0, s57, 0x1c00
	v_lshl_add_u64 v[202:203], v[192:193], 0, s[12:13]
	s_ashr_i32 s11, s10, 31
	s_add_i32 s12, s87, 0xffffc400
	s_add_i32 s88, s87, 0xffffc800
	global_load_lds_dwordx4 v[2:3], off
	v_lshl_add_u64 v[2:3], v[202:203], 0, s[10:11]
	s_ashr_i32 s13, s12, 31
	s_ashr_i32 s89, s88, 31
	s_add_i32 s90, s87, 0xffffcc00
	s_add_i32 s92, s87, 0xffffd000
	s_ashr_i32 s27, s26, 31
	v_lshl_add_u64 v[4:5], v[202:203], 0, s[12:13]
	global_load_dwordx4 v[96:99], v[2:3], off
	global_load_dwordx4 v[100:103], v[4:5], off
	v_lshl_add_u64 v[2:3], v[202:203], 0, s[88:89]
	s_ashr_i32 s91, s90, 31
	s_ashr_i32 s93, s92, 31
	s_add_i32 s94, s87, 0xffffd400
	s_add_i32 s96, s87, 0xffffd800
	s_lshl_b64 s[26:27], s[26:27], 23
	v_lshl_add_u64 v[4:5], v[202:203], 0, s[90:91]
	global_load_dwordx4 v[104:107], v[2:3], off
	global_load_dwordx4 v[108:111], v[4:5], off
	v_lshl_add_u64 v[2:3], v[202:203], 0, s[92:93]
	s_ashr_i32 s95, s94, 31
	s_ashr_i32 s97, s96, 31
	s_add_i32 vcc_lo, s87, 0xffffdc00
	v_lshl_add_u64 v[4:5], v[202:203], 0, s[94:95]
	global_load_dwordx4 v[120:123], v[2:3], off
	global_load_dwordx4 v[124:127], v[4:5], off
	v_lshl_add_u64 v[2:3], v[202:203], 0, s[96:97]
	s_ashr_i32 vcc_hi, vcc_lo, 31
	v_lshl_add_u64 v[204:205], v[192:193], 0, s[26:27]
	v_lshl_add_u64 v[4:5], v[202:203], 0, vcc
	global_load_dwordx4 v[168:171], v[2:3], off
	global_load_dwordx4 v[172:175], v[4:5], off
	v_lshl_add_u64 v[2:3], v[204:205], 0, s[10:11]
	v_lshl_add_u64 v[4:5], v[204:205], 0, s[12:13]
	global_load_dwordx4 v[112:115], v[2:3], off
	global_load_dwordx4 v[116:119], v[4:5], off
	v_lshl_add_u64 v[2:3], v[204:205], 0, s[88:89]
	v_lshl_add_u64 v[4:5], v[204:205], 0, s[90:91]
	global_load_dwordx4 v[144:147], v[2:3], off
	global_load_dwordx4 v[156:159], v[4:5], off
	v_lshl_add_u64 v[2:3], v[204:205], 0, s[92:93]
	v_lshl_add_u64 v[4:5], v[204:205], 0, s[94:95]
	global_load_dwordx4 v[176:179], v[2:3], off
	global_load_dwordx4 v[180:183], v[4:5], off
	v_lshl_add_u64 v[2:3], v[204:205], 0, s[96:97]
	v_lshl_add_u64 v[4:5], v[204:205], 0, vcc
	global_load_dwordx4 v[184:187], v[2:3], off
	global_load_dwordx4 v[188:191], v[4:5], off
	v_mov_b32_e32 v0, v218
	s_waitcnt vmcnt(16)
	s_add_i32 s10, s85, s33
	v_xor_b32_e32 v8, 0xe0, v0
	v_xor_b32_e32 v2, 32, v0
	v_xor_b32_e32 v3, 64, v0
	v_xor_b32_e32 v4, 0x60, v0
	v_xor_b32_e32 v5, 0x80, v0
	v_xor_b32_e32 v6, 0xa0, v0
	v_xor_b32_e32 v7, 0xc0, v0
	ds_read_b128 v[128:131], v8
	ds_read_b128 v[132:135], v7
	ds_read_b128 v[136:139], v6
	ds_read_b128 v[140:143], v5
	ds_read_b128 v[148:151], v4
	ds_read_b128 v[152:155], v3
	ds_read_b128 v[160:163], v2
	ds_read_b128 v[164:167], v0
	s_waitcnt lgkmcnt(0)
	s_waitcnt lgkmcnt(0)
	v_mov_b32_e32 v14, v1
	v_mov_b32_e32 v15, v1
	s_lshl_b32 s10, s10, 8
	v_mov_b32_e32 v0, v1
	v_mov_b32_e32 v2, v1
	v_mov_b32_e32 v3, v1
	v_mov_b32_e32 v4, v1
	v_mov_b32_e32 v5, v1
	v_mov_b32_e32 v6, v1
	v_mov_b32_e32 v7, v1
	v_mov_b32_e32 v8, v1
	v_mov_b32_e32 v9, v1
	v_mov_b32_e32 v10, v1
	v_mov_b32_e32 v11, v1
	v_mov_b32_e32 v12, v1
	v_mov_b32_e32 v13, v1
	s_waitcnt vmcnt(0)
	v_mov_b64_e32 v[30:31], v[14:15]
	v_mov_b64_e32 v[46:47], v[14:15]
	v_mov_b64_e32 v[62:63], v[14:15]
	v_mov_b64_e32 v[78:79], v[14:15]
	s_lshl_b32 s87, s100, 5
	s_mov_b32 s99, 0
	v_add_u32_e32 v236, s85, v215
	s_add_i32 s12, s79, s10
	s_mul_i32 s101, s100, 0x2000
	s_add_i32 s12, s12, s101
	s_cmp_eq_u32 s100, 4
	s_cselect_b32 s101, 0xffff6000, 0
	s_add_i32 s12, s12, s101
	v_mov_b32_e32 v237, 0
	v_mov_b32_e32 v238, 0xf149f2ca
	v_mov_b64_e32 v[28:29], v[12:13]
	v_mov_b64_e32 v[26:27], v[10:11]
	v_mov_b64_e32 v[24:25], v[8:9]
	v_mov_b64_e32 v[22:23], v[6:7]
	v_mov_b64_e32 v[20:21], v[4:5]
	v_mov_b64_e32 v[18:19], v[2:3]
	v_mov_b64_e32 v[16:17], v[0:1]
	v_mov_b64_e32 v[44:45], v[12:13]
	v_mov_b64_e32 v[42:43], v[10:11]
	v_mov_b64_e32 v[40:41], v[8:9]
	v_mov_b64_e32 v[38:39], v[6:7]
	v_mov_b64_e32 v[36:37], v[4:5]
	v_mov_b64_e32 v[34:35], v[2:3]
	v_mov_b64_e32 v[32:33], v[0:1]
	v_mov_b64_e32 v[60:61], v[12:13]
	v_mov_b64_e32 v[58:59], v[10:11]
	v_mov_b64_e32 v[56:57], v[8:9]
	v_mov_b64_e32 v[54:55], v[6:7]
	v_mov_b64_e32 v[52:53], v[4:5]
	v_mov_b64_e32 v[50:51], v[2:3]
	v_mov_b64_e32 v[48:49], v[0:1]
	v_mov_b64_e32 v[76:77], v[12:13]
	v_mov_b64_e32 v[74:75], v[10:11]
	v_mov_b64_e32 v[72:73], v[8:9]
	v_mov_b64_e32 v[70:71], v[6:7]
	v_mov_b64_e32 v[68:69], v[4:5]
	v_mov_b64_e32 v[66:67], v[2:3]
	v_mov_b64_e32 v[64:65], v[0:1]
; #define ATT_STAGE_K() do { unsigned kD_ = kD; asm volatile("" : "+v"(kD_));     \
;         _Pragma("unroll") for (int c = 0; c < 8; ++c) *(ALDS u32x4*)((kD_ ^ (unsigned)((c & 3) << 6)) + 1024u * c) = kr[c]; asm volatile("" ::: "memory"); } while (0)
; #define DIL_LOAD(t, dst, src) do { const int mk0_ = m0 - 64 + 32 * (t); \
;             _Pragma("unroll") for (int c = 0; c < 8; ++c) { const int uo_ = (rbase + mk0_ + 4 * c) * (int)(PITCH * 2); dst[c] = *(const u32x4*)((src + (long)uo_) + lane_off); } } while (0)
; __device__ __forceinline__ void dil_phase(const bf16* qkv, bf16* scratch, bf16* merged, ldsp lds, int vcu, int G, int tid_in) {
;     ...
;             for (int t = 0; t < 5; ++t) {
;                 ATT_STAGE_K();
;                 ATT_QK();
;                 if (t + 1 < 5) DIL_LOAD(t + 1, kr, kb);
.LBB0_683:
	v_add_u32_e32 v0, s57, v214
	s_waitcnt vmcnt(7)
	ds_write_b128 v0, v[96:99]
	v_xor_b32_e32 v2, 64, v0
	v_xor_b32_e32 v3, 0x80, v0
	v_xor_b32_e32 v4, 0xc0, v0
	s_waitcnt vmcnt(6)
	ds_write_b128 v2, v[100:103] offset:1024
	s_waitcnt vmcnt(5)
	ds_write_b128 v3, v[104:107] offset:2048
	s_waitcnt vmcnt(4)
	ds_write_b128 v4, v[108:111] offset:3072
	s_waitcnt vmcnt(3)
	ds_write_b128 v0, v[120:123] offset:4096
	s_waitcnt vmcnt(2)
	ds_write_b128 v2, v[124:127] offset:5120
	s_waitcnt vmcnt(1)
	ds_write_b128 v3, v[168:171] offset:6144
	s_waitcnt vmcnt(0)
	ds_write_b128 v4, v[172:175] offset:7168
	v_mov_b32_e32 v0, v218
	s_cmp_lg_u32 s99, 4
	v_xor_b32_e32 v80, 0x60, v0
	v_xor_b32_e32 v81, 0x80, v0
	v_xor_b32_e32 v10, 0xa0, v0
	v_xor_b32_e32 v6, 0xc0, v0
	v_xor_b32_e32 v2, 0xe0, v0
	v_xor_b32_e32 v14, 32, v0
	v_xor_b32_e32 v15, 64, v0
	ds_read_b128 v[2:5], v2
	ds_read_b128 v[6:9], v6
	ds_read_b128 v[10:13], v10
	ds_read_b128 v[206:209], v81
	ds_read_b128 v[240:243], v80
	ds_read_b128 v[244:247], v15
	ds_read_b128 v[248:251], v14
	ds_read_b128 v[80:83], v0
	s_waitcnt lgkmcnt(0)
	s_waitcnt lgkmcnt(0)
	s_nop 0
	v_mfma_f32_32x32x16_bf16 v[80:95], v[80:83], v[164:167], 0
	s_cselect_b64 s[10:11], -1, 0
	s_cmp_eq_u32 s99, 4
	v_mfma_f32_32x32x16_bf16 v[80:95], v[248:251], v[160:163], v[80:95]
	v_mfma_f32_32x32x16_bf16 v[80:95], v[244:247], v[152:155], v[80:95]
	v_mfma_f32_32x32x16_bf16 v[80:95], v[240:243], v[148:151], v[80:95]
	v_mfma_f32_32x32x16_bf16 v[80:95], v[206:209], v[140:143], v[80:95]
	v_mfma_f32_32x32x16_bf16 v[80:95], v[10:13], v[136:139], v[80:95]
	v_mfma_f32_32x32x16_bf16 v[80:95], v[6:9], v[132:135], v[80:95]
	v_mfma_f32_32x32x16_bf16 v[80:95], v[2:5], v[128:131], v[80:95]
	s_cbranch_scc1 .LBB0_685
	s_add_i32 s26, s12, 0xfffff000
	s_ashr_i32 s27, s26, 31
	v_lshl_add_u64 v[2:3], v[202:203], 0, s[26:27]
	s_add_i32 s26, s12, 0xfffff400
	s_ashr_i32 s27, s26, 31
	v_lshl_add_u64 v[4:5], v[202:203], 0, s[26:27]
	s_add_i32 s26, s12, 0xfffff800
	s_ashr_i32 s27, s26, 31
	global_load_dwordx4 v[96:99], v[2:3], off
	global_load_dwordx4 v[100:103], v[4:5], off
	v_lshl_add_u64 v[2:3], v[202:203], 0, s[26:27]
	s_add_i32 s26, s12, 0xfffffc00
	s_ashr_i32 s27, s26, 31
	v_lshl_add_u64 v[4:5], v[202:203], 0, s[26:27]
	s_add_i32 s26, s12, 0x400
	s_ashr_i32 s27, s26, 31
	global_load_dwordx4 v[104:107], v[2:3], off
	global_load_dwordx4 v[108:111], v[4:5], off
	s_ashr_i32 s13, s12, 31
	v_lshl_add_u64 v[4:5], v[202:203], 0, s[26:27]
	s_add_i32 s26, s12, 0x800
	v_lshl_add_u64 v[2:3], v[202:203], 0, s[12:13]
	s_ashr_i32 s27, s26, 31
	global_load_dwordx4 v[120:123], v[2:3], off
	global_load_dwordx4 v[124:127], v[4:5], off
	v_lshl_add_u64 v[2:3], v[202:203], 0, s[26:27]
	s_add_i32 s26, s12, 0xc00
	s_ashr_i32 s27, s26, 31
	v_lshl_add_u64 v[4:5], v[202:203], 0, s[26:27]
	global_load_dwordx4 v[168:171], v[2:3], off
	global_load_dwordx4 v[172:175], v[4:5], off

; #define ALDS __attribute__((address_space(3)))
; __device__ __forceinline__ unsigned cvtpk(float lo, float hi) { f32x2_t v = {lo, hi}; bf16x2_t b = __builtin_convertvector(v, bf16x2_t); return __builtin_bit_cast(unsigned, b); }
; __device__ __forceinline__ s16x4 vtr(ALDS const unsigned char* p) { return __builtin_bit_cast(s16x4, __builtin_amdgcn_ds_read_tr16_b64_v4i16((ALDS v4i16_t*)p)); }
; __device__ __forceinline__ void softmax_pv(f32x16& st, const unsigned (&trB)[2], St& S) {
;     ...
;     for (int s = 0; s < 2; ++s) {
;         u32x4 pw; pw.x = cvtpk(st[8 * s + 0], st[8 * s + 1]); pw.y = cvtpk(st[8 * s + 2], st[8 * s + 3]); pw.z = cvtpk(st[8 * s + 4], st[8 * s + 5]); pw.w = cvtpk(st[8 * s + 6], st[8 * s + 7]);
;         const bf16x8 pf = __builtin_bit_cast(bf16x8, pw);
; #pragma unroll
;         for (int db = 0; db < 4; ++db) {
;             const s16x4 a0 = vtr((ALDS const unsigned char*)((tb0 ^ (unsigned)(db << 6)) + 4096u * s)), a1 = vtr((ALDS const unsigned char*)((tb1 ^ (unsigned)(db << 6)) + 4096u * s));
;             const bf16x8 vf = {a0[0], a0[1], a0[2], a0[3], a1[0], a1[1], a1[2], a1[3]};
;             S.O[db] = __builtin_amdgcn_mfma_f32_32x32x16_bf16(vf, pf, S.O[db], 0, 0, 0);
;         }
;     }
; __device__ __forceinline__ void dil_phase(const bf16* qkv, bf16* scratch, bf16* merged, ldsp lds, int vcu, int G, int tid_in) {
;     ...
;             for (int t = 0; t < 5; ++t) {
.LBB0_689:
	v_mov_b32_e32 v94, v217
	v_mov_b32_e32 v95, v216
	ds_read_b64_tr_b16 v[86:87], v95
	ds_read_b64_tr_b16 v[88:89], v94
	v_cvt_pk_bf16_f32 v90, v13, v14
	v_cvt_pk_bf16_f32 v91, v15, v80
	v_cvt_pk_bf16_f32 v92, v81, v82
	v_cvt_pk_bf16_f32 v93, v83, v84
	v_xor_b32_e32 v14, 64, v94
	ds_read_b64_tr_b16 v[80:81], v95 offset:4096
	ds_read_b64_tr_b16 v[82:83], v94 offset:4096
	s_waitcnt lgkmcnt(2)
	v_mfma_f32_32x32x16_bf16 v[64:79], v[86:89], v[90:93], v[64:79]
	v_xor_b32_e32 v13, 64, v95
	ds_read_b64_tr_b16 v[86:87], v14
	ds_read_b64_tr_b16 v[84:85], v13
	ds_read_b64_tr_b16 v[206:207], v13 offset:4096
	ds_read_b64_tr_b16 v[208:209], v14 offset:4096
	v_xor_b32_e32 v14, 0x80, v94
	v_xor_b32_e32 v13, 0x80, v95
	v_cvt_pk_bf16_f32 v4, v3, v4
	v_cvt_pk_bf16_f32 v5, v5, v6
	v_cvt_pk_bf16_f32 v6, v7, v8
	s_waitcnt lgkmcnt(2)
	v_mfma_f32_32x32x16_bf16 v[48:63], v[84:87], v[90:93], v[48:63]
	ds_read_b64_tr_b16 v[86:87], v14
	ds_read_b64_tr_b16 v[84:85], v13
	ds_read_b64_tr_b16 v[238:239], v13 offset:4096
	ds_read_b64_tr_b16 v[240:241], v14 offset:4096
	v_xor_b32_e32 v14, 0xc0, v94
	v_xor_b32_e32 v13, 0xc0, v95
	v_cvt_pk_bf16_f32 v7, v9, v11
	v_add_f32_e32 v3, v10, v12
	s_add_i32 s87, s87, 32
	s_addk_i32 s12, 0x2000
	s_waitcnt lgkmcnt(2)
	v_mfma_f32_32x32x16_bf16 v[32:47], v[84:87], v[90:93], v[32:47]
	ds_read_b64_tr_b16 v[86:87], v14
	ds_read_b64_tr_b16 v[84:85], v13
	ds_read_b64_tr_b16 v[242:243], v13 offset:4096
	ds_read_b64_tr_b16 v[244:245], v14 offset:4096
	v_fmac_f32_e32 v3, v237, v0
	s_add_i32 s99, s99, 1
	s_cmpk_eq_i32 s87, 0xa0
	s_cselect_b32 s87, 0, s87
	s_cmpk_eq_i32 s87, 0x80
	s_cselect_b32 s101, 0xffff6000, 0
	s_add_i32 s12, s12, s101
	s_cmp_eq_u32 s99, 5
	s_waitcnt lgkmcnt(2)
	v_mfma_f32_32x32x16_bf16 v[16:31], v[84:87], v[90:93], v[16:31]
	v_mfma_f32_32x32x16_bf16 v[64:79], v[80:83], v[4:7], v[64:79]
	v_mfma_f32_32x32x16_bf16 v[48:63], v[206:209], v[4:7], v[48:63]
	v_mfma_f32_32x32x16_bf16 v[32:47], v[238:241], v[4:7], v[32:47]
	s_waitcnt lgkmcnt(0)
	v_mfma_f32_32x32x16_bf16 v[16:31], v[242:245], v[4:7], v[16:31]
	s_cbranch_scc1 .LBB0_691
	v_mov_b32_e32 v238, v2
	v_mov_b32_e32 v237, v3
	s_branch .LBB0_683
